# grid barrier: XCD leader arrives on the top counter without waiting for the return; all workgroups poll the top arrival counter
# baseline (speedup 1.0000x reference)
; __device__ __forceinline__ unsigned xb_add(unsigned* p, unsigned v) { return __hip_atomic_fetch_add(p, v, __ATOMIC_RELAXED, __HIP_MEMORY_SCOPE_AGENT); }
; __device__ __forceinline__ void xcd_barrier(const XcdBarrier& b) {
;     ...
;         const unsigned old = xb_add(&bar[XB_XSUB(b.x)], 1u);
;         const unsigned gen = old / nloc;
;         if (old + 1u == (gen + 1u) * nloc) {
;             __builtin_amdgcn_fence(__ATOMIC_RELEASE, "agent");
;             asm volatile("s_waitcnt vmcnt(0)" ::: "memory");
;             const unsigned og = xb_add(&bar[XB_TOP], 1u);
;             const unsigned tg = og / nx;
;             if (og + 1u == (tg + 1u) * nx) xb_add(&bar[XB_TOPGEN], 1u);
.LBB0_1038:
	s_or_b64 exec, exec, s[6:7]
	v_cvt_f32_u32_e32 v5, v3
	s_waitcnt vmcnt(0)
	v_readfirstlane_b32 s4, v4
	v_sub_u32_e32 v4, 0, v3
	v_rcp_iflag_f32_e32 v5, v5
	v_add_u32_e32 v6, s4, v0
	v_mul_f32_e32 v5, 0x4f7ffffe, v5
	v_cvt_u32_f32_e32 v5, v5
	v_mul_lo_u32 v0, v4, v5
	v_mul_hi_u32 v0, v5, v0
	v_add_u32_e32 v0, v5, v0
	v_mul_hi_u32 v0, v6, v0
	v_mul_lo_u32 v4, v0, v3
	v_sub_u32_e32 v4, v6, v4
	v_add_u32_e32 v5, 1, v0
	v_cmp_ge_u32_e32 vcc, v4, v3
	s_nop 1
	v_cndmask_b32_e32 v0, v0, v5, vcc
	v_sub_u32_e32 v5, v4, v3
	v_cndmask_b32_e32 v4, v4, v5, vcc
	v_add_u32_e32 v5, 1, v0
	v_cmp_ge_u32_e32 vcc, v4, v3
	v_add_u32_e32 v4, 1, v6
	s_nop 0
	v_cndmask_b32_e32 v0, v0, v5, vcc
	v_mul_lo_u32 v5, v3, v0
	v_add_u32_e32 v3, v5, v3
	v_cmp_ne_u32_e32 vcc, v4, v3
	s_cbranch_vccnz .Lxb_wait
	buffer_wbl2 sc1
	buffer_inv sc1
	s_waitcnt vmcnt(0)
	v_mov_b32_e32 v4, 0x3000
	v_mov_b32_e32 v5, 1
	global_atomic_add v4, v5, s[90:91] offset:1024
	s_branch .Lxb_poll

; __device__ __forceinline__ unsigned xb_ld(unsigned* p)              { return __hip_atomic_load(p, __ATOMIC_RELAXED, __HIP_MEMORY_SCOPE_AGENT); }
; __device__ __forceinline__ unsigned xb_add(unsigned* p, unsigned v) { return __hip_atomic_fetch_add(p, v, __ATOMIC_RELAXED, __HIP_MEMORY_SCOPE_AGENT); }
; #define XB_SPIN(cond, bar) do { unsigned _sp = 0; while (cond) { __builtin_amdgcn_s_sleep(1); \
;     if ((++_sp & 255u) == 0u) { if (xb_ld(&(bar)[XB_TMO])) break; if (_sp > XB_SPIN_CAP) { atomicAdd(&(bar)[XB_TMO], 1u); break; } } } } while (0)
; __device__ __forceinline__ void xcd_barrier(const XcdBarrier& b) {
;     ...
;             const unsigned og = xb_add(&bar[XB_TOP], 1u);
;             const unsigned tg = og / nx;
;             if (og + 1u == (tg + 1u) * nx) xb_add(&bar[XB_TOPGEN], 1u);
;             else XB_SPIN(xb_ld(&bar[XB_TOPGEN]) == tg, bar);
;             __builtin_amdgcn_fence(__ATOMIC_ACQUIRE, "agent");
;             xb_add(&bar[XB_XGEN(b.x)], 1u);
;             asm volatile("s_waitcnt vmcnt(0)" ::: "memory");
;         } else {
;             XB_SPIN(xb_ld(&bar[XB_XGEN(b.x)]) == gen, bar);
;             __builtin_amdgcn_fence(__ATOMIC_ACQUIRE, "agent");
;             asm volatile("s_waitcnt vmcnt(0)" ::: "memory");
;         }
.Lxb_poll:
	s_waitcnt lgkmcnt(0)
	v_add_u32_e32 v5, 1, v0
	v_mul_lo_u32 v5, v5, v2
	s_add_u32 s8, s90, 0x3400
	s_addc_u32 s9, s91, 0
	s_mov_b32 s20, 0
.Lxb_spin:
	global_load_dword v4, v1, s[8:9] sc1
	s_waitcnt vmcnt(0)
	v_cmp_le_u32_e32 vcc, v5, v4
	s_cbranch_vccnz .Lxb_released
	s_sleep 1
	s_add_i32 s20, s20, 1
	s_and_b32 s16, s20, 0xff
	s_cmp_lg_u32 s16, 0
	s_cbranch_scc1 .Lxb_spin
	global_load_dword v4, v1, s[90:91] offset:512 sc1
	s_waitcnt vmcnt(0)
	v_cmp_ne_u32_e32 vcc, 0, v4
	s_cbranch_vccnz .Lxb_released
	s_cmp_lt_u32 s20, 0x40001
	s_cbranch_scc1 .Lxb_spin
	v_mov_b32_e32 v4, 1
	global_atomic_add v1, v4, s[90:91] offset:512
.Lxb_released:
	s_waitcnt vmcnt(0)
	s_getpc_b64 s[98:99]
